# prompt-attention unmasked fast path re-scheduled by hand: QK^T of keys 0-31 first, exp of that half under the MFMAs of keys 32-63, second-half exp under P.V, row sums under the last P.V
# speedup vs baseline: 1.0037x; 1.0037x over previous
; #define LAS __attribute__((address_space(3)))
; #define MFMA32(a, b, c) __builtin_amdgcn_mfma_f32_32x32x16_bf16((a), (b), (c), 0, 0, 0)
; DI int crow(int r, int hi) { return (r & 3) + 8 * (r >> 2) + 4 * hi; }
; DI void attn_prompt_unit(const Args& a, LAS unsigned char* lds, int b, int h, int qb, float cB, int tid, int lane, int wave) {
;     ...
;     for (int t = 0; t < NT; ++t) {
;         const int buf = t & 1;
;         if (t + 1 < NT) { const size_t kv1 = (size_t)(t + 1) * 64;
;             kst0 = *(const u32x4*)(kbase + (kv1 + kr0) * 768 + kp0 * 8); if (k1) kst1 = *(const u32x4*)(kbase + (kv1 + kr1) * 768 + kp1 * 8); vst = *(const u32x4*)(vbase + kv1 * 1024); }
;         if (t * 64 <= qmax_w) {
;             const LAS bf16* Kb = Ks + buf * 6656; const LAS bf16* Vb = Vs + buf * 6144;
;             f32x16 p0, p1;
; #pragma unroll
;             for (int r = 0; r < 16; ++r) { p0[r] = -cB; p1[r] = -cB; }
; #pragma unroll
;             for (int s = 0; s < 6; ++s) { const bf16x8 k0 = *(const LAS bf16x8*)(Kb + r32 * 104 + 16 * s + 8 * h2), k1f = *(const LAS bf16x8*)(Kb + (32 + r32) * 104 + 16 * s + 8 * h2);
;                 p0 = MFMA32(k0, qf[s], p0); p1 = MFMA32(k1f, qf[s], p1); }
;             const bool diag = (t * 64 + 63 > qb * 256 + wave * 32);
; #pragma unroll
;             for (int r = 0; r < 16; ++r) { const int kv = t * 64 + crow(r, h2);
;                 float e0 = __builtin_amdgcn_exp2f(p0[r]), e1 = __builtin_amdgcn_exp2f(p1[r]);
;                 if (diag) { if (kv > qloc) e0 = 0.f; if (kv + 32 > qloc) e1 = 0.f; }
;                 p0[r] = e0; p1[r] = e1; lsum += e0 + e1; }
; #pragma unroll
;             for (int s4 = 0; s4 < 4; ++s4) { const bf16x8 pf = (s4 < 2) ? pack8(p0, s4 & 1) : pack8(p1, s4 & 1);
;                 o0 = MFMA32(tr_frag(Vb, 96, 16 * s4 + 4 * h2, 16 * s4 + 8 + 4 * h2, 0, lane), pf, o0); o1 = MFMA32(tr_frag(Vb, 96, 16 * s4 + 4 * h2, 16 * s4 + 8 + 4 * h2, 32, lane), pf, o1); }
.LBB0_841:
	s_or_b64 exec, exec, s[4:5]
	global_load_dwordx4 v[114:117], v[184:185], off
	s_and_b32 s36, s35, 1
	s_cmp_gt_i32 s34, s31
	s_cbranch_scc1 .LBB0_843
	s_add_i32 s4, s34, 63
	s_cmp_gt_i32 s4, s29
	s_cselect_b64 s[20:21], -1, 0
	s_cbranch_scc0 .Lpa_fast_0
	s_mul_i32 s4, s36, 0x3400
	s_add_i32 s4, s4, 0
	v_add3_u32 v119, s4, v227, v126
	ds_read_b128 v[50:53], v119
	ds_read_b128 v[186:189], v119 offset:32
	v_add3_u32 v121, s4, v228, v126
	ds_read_b128 v[190:193], v121
	ds_read_b128 v[194:197], v121 offset:32
	s_add_i32 s4, s34, 63
	s_cmp_gt_i32 s4, s29
	s_cselect_b64 s[20:21], -1, 0
	s_mul_i32 s37, s36, 0x3000
	s_waitcnt lgkmcnt(3)
	v_mfma_f32_32x32x16_bf16 v[66:81], v[50:53], v[86:89], v[2:17]
	s_waitcnt lgkmcnt(1)
	v_mfma_f32_32x32x16_bf16 v[50:65], v[190:193], v[86:89], v[2:17]
	v_mfma_f32_32x32x16_bf16 v[66:81], v[186:189], v[90:93], v[66:81]
	ds_read_b128 v[186:189], v119 offset:64
	ds_read_b128 v[190:193], v119 offset:96
	s_waitcnt lgkmcnt(2)
	v_mfma_f32_32x32x16_bf16 v[50:65], v[194:197], v[90:93], v[50:65]
	s_waitcnt lgkmcnt(1)
	v_mfma_f32_32x32x16_bf16 v[66:81], v[186:189], v[94:97], v[66:81]
	ds_read_b128 v[186:189], v121 offset:64
	ds_read_b128 v[194:197], v121 offset:96
	s_waitcnt lgkmcnt(1)
	v_mfma_f32_32x32x16_bf16 v[50:65], v[186:189], v[94:97], v[50:65]
	v_mfma_f32_32x32x16_bf16 v[66:81], v[190:193], v[98:101], v[66:81]
	ds_read_b128 v[186:189], v119 offset:128
	ds_read_b128 v[190:193], v119 offset:160
	v_add_u32_e32 v119, s34, v118
	v_cmp_gt_i32_e32 vcc, v119, v178
	s_and_b64 s[38:39], s[20:21], vcc
	v_cmp_ge_i32_e32 vcc, v119, v178
	s_waitcnt lgkmcnt(2)
	v_mfma_f32_32x32x16_bf16 v[50:65], v[194:197], v[98:101], v[50:65]
	s_waitcnt lgkmcnt(1)
	v_mfma_f32_32x32x16_bf16 v[66:81], v[186:189], v[106:109], v[66:81]
	ds_read_b128 v[186:189], v121 offset:128
	ds_read_b128 v[194:197], v121 offset:160
	v_add_u32_e32 v121, 32, v119
	v_cmp_gt_i32_e64 s[4:5], v121, v178
	s_and_b64 s[4:5], s[20:21], s[4:5]
	s_waitcnt lgkmcnt(1)
	v_mfma_f32_32x32x16_bf16 v[50:65], v[186:189], v[106:109], v[50:65]
	s_waitcnt lgkmcnt(0)
	v_mfma_f32_32x32x16_bf16 v[50:65], v[194:197], v[102:105], v[50:65]
	v_mfma_f32_32x32x16_bf16 v[66:81], v[190:193], v[102:105], v[66:81]
	s_nop 10
	v_exp_f32_e32 v50, v50
	v_exp_f32_e32 v51, v51
	v_exp_f32_e32 v52, v52
	v_exp_f32_e32 v64, v64
	v_cndmask_b32_e64 v121, v50, 0, s[4:5]
	v_exp_f32_e32 v65, v65
	v_exp_f32_e32 v66, v66
	v_exp_f32_e32 v50, v67
	v_add_u32_e32 v67, 33, v119
	v_cmp_gt_i32_e64 s[4:5], v67, v178
	v_cndmask_b32_e64 v66, v66, 0, s[38:39]
	s_and_b64 s[38:39], s[20:21], vcc
	s_and_b64 s[4:5], s[20:21], s[4:5]
	v_cndmask_b32_e64 v67, v50, 0, s[38:39]
	v_cndmask_b32_e64 v133, v51, 0, s[4:5]
	v_add_u32_e32 v50, 2, v119
	v_exp_f32_e32 v51, v68
	v_cmp_gt_i32_e32 vcc, v50, v178
	v_add_u32_e32 v50, 34, v119
	v_cmp_gt_i32_e64 s[4:5], v50, v178
	s_and_b64 s[38:39], s[20:21], vcc
	s_and_b64 s[4:5], s[20:21], s[4:5]
	v_cndmask_b32_e64 v68, v51, 0, s[38:39]
	v_cndmask_b32_e64 v137, v52, 0, s[4:5]
	v_add_u32_e32 v50, 3, v119
	v_exp_f32_e32 v51, v69
	v_exp_f32_e32 v52, v53
	v_cmp_gt_i32_e32 vcc, v50, v178
	v_add_u32_e32 v50, 35, v119
	v_cmp_gt_i32_e64 s[4:5], v50, v178
	s_and_b64 s[38:39], s[20:21], vcc
	s_and_b64 s[4:5], s[20:21], s[4:5]
	v_cndmask_b32_e64 v69, v51, 0, s[38:39]
	v_cndmask_b32_e64 v157, v52, 0, s[4:5]
	v_add_u32_e32 v50, 8, v119
	v_exp_f32_e32 v51, v70
	v_exp_f32_e32 v52, v54
	v_cmp_gt_i32_e32 vcc, v50, v178
	v_add_u32_e32 v50, 40, v119
	v_cmp_gt_i32_e64 s[4:5], v50, v178
	s_and_b64 s[38:39], s[20:21], vcc
	s_and_b64 s[4:5], s[20:21], s[4:5]
	v_cndmask_b32_e64 v70, v51, 0, s[38:39]
	v_cndmask_b32_e64 v161, v52, 0, s[4:5]
	v_add_u32_e32 v50, 9, v119
	v_exp_f32_e32 v51, v71
	v_exp_f32_e32 v52, v55
	v_cmp_gt_i32_e32 vcc, v50, v178
	v_add_u32_e32 v50, 41, v119
	v_cmp_gt_i32_e64 s[4:5], v50, v178
	s_and_b64 s[38:39], s[20:21], vcc
	s_and_b64 s[4:5], s[20:21], s[4:5]
	v_cndmask_b32_e64 v71, v51, 0, s[38:39]
	v_cndmask_b32_e64 v171, v52, 0, s[4:5]
	v_add_u32_e32 v50, 10, v119
	v_exp_f32_e32 v51, v72
	v_exp_f32_e32 v52, v56
	v_cmp_gt_i32_e32 vcc, v50, v178
	v_add_u32_e32 v50, 42, v119
	v_cmp_gt_i32_e64 s[4:5], v50, v178
	s_and_b64 s[38:39], s[20:21], vcc
	s_and_b64 s[4:5], s[20:21], s[4:5]
	v_cndmask_b32_e64 v72, v51, 0, s[38:39]
	v_cndmask_b32_e64 v186, v52, 0, s[4:5]
	v_add_u32_e32 v50, 11, v119
	v_exp_f32_e32 v51, v73
	v_exp_f32_e32 v52, v57
	v_cmp_gt_i32_e32 vcc, v50, v178
	v_add_u32_e32 v50, 43, v119
	v_cmp_gt_i32_e64 s[4:5], v50, v178
	s_and_b64 s[38:39], s[20:21], vcc
	s_and_b64 s[4:5], s[20:21], s[4:5]
	v_cndmask_b32_e64 v57, v51, 0, s[38:39]
	v_cndmask_b32_e64 v73, v52, 0, s[4:5]
	v_add_u32_e32 v50, 16, v119
	v_exp_f32_e32 v51, v74
	v_exp_f32_e32 v52, v58
	v_cmp_gt_i32_e32 vcc, v50, v178
	v_add_u32_e32 v50, 48, v119
	v_cmp_gt_i32_e64 s[4:5], v50, v178
	s_and_b64 s[38:39], s[20:21], vcc
	s_and_b64 s[4:5], s[20:21], s[4:5]
	v_cndmask_b32_e64 v74, v51, 0, s[38:39]
	v_cndmask_b32_e64 v189, v52, 0, s[4:5]
	v_add_u32_e32 v50, 17, v119
	v_exp_f32_e32 v51, v75
	v_exp_f32_e32 v52, v59
	v_cmp_gt_i32_e32 vcc, v50, v178
	v_add_u32_e32 v50, 49, v119
	v_cmp_gt_i32_e64 s[4:5], v50, v178
	s_and_b64 s[38:39], s[20:21], vcc
	s_and_b64 s[4:5], s[20:21], s[4:5]
	v_cndmask_b32_e64 v75, v51, 0, s[38:39]
	v_cndmask_b32_e64 v191, v52, 0, s[4:5]
	v_add_u32_e32 v50, 18, v119
	v_exp_f32_e32 v51, v76
	v_exp_f32_e32 v52, v60
	v_cmp_gt_i32_e32 vcc, v50, v178
	v_add_u32_e32 v50, 50, v119
	v_cmp_gt_i32_e64 s[4:5], v50, v178
	s_and_b64 s[38:39], s[20:21], vcc
	s_and_b64 s[4:5], s[20:21], s[4:5]
	v_cndmask_b32_e64 v76, v51, 0, s[38:39]
	v_cndmask_b32_e64 v192, v52, 0, s[4:5]
	v_add_u32_e32 v50, 19, v119
	v_exp_f32_e32 v51, v77
	v_exp_f32_e32 v52, v61
	v_cmp_gt_i32_e32 vcc, v50, v178
	v_add_u32_e32 v50, 51, v119
	v_cmp_gt_i32_e64 s[4:5], v50, v178
	s_and_b64 s[38:39], s[20:21], vcc
	s_and_b64 s[4:5], s[20:21], s[4:5]
	v_cndmask_b32_e64 v77, v51, 0, s[38:39]
	v_cndmask_b32_e64 v193, v52, 0, s[4:5]
	v_add_u32_e32 v50, 24, v119
	v_exp_f32_e32 v51, v78
	v_exp_f32_e32 v52, v62
	v_cmp_gt_i32_e32 vcc, v50, v178
	v_add_u32_e32 v50, 56, v119
	v_cmp_gt_i32_e64 s[4:5], v50, v178
	s_and_b64 s[38:39], s[20:21], vcc
	s_and_b64 s[4:5], s[20:21], s[4:5]
	v_add_u32_e32 v50, 25, v119
	v_exp_f32_e32 v54, v79
	v_add_u32_e32 v79, s37, v229
	v_cndmask_b32_e64 v62, v51, 0, s[38:39]
	v_cndmask_b32_e64 v78, v52, 0, s[4:5]
	v_cmp_gt_i32_e32 vcc, v50, v178
	ds_read_b64_tr_b16 v[50:51], v79 offset:26624
	ds_read_b64_tr_b16 v[52:53], v79 offset:28160
	ds_read_b64_tr_b16 v[60:61], v79 offset:28224
	ds_read_b64_tr_b16 v[58:59], v79 offset:26688
	s_and_b64 s[4:5], s[20:21], vcc
	v_add_f32_e32 v188, v57, v73
	v_cndmask_b32_e64 v194, v54, 0, s[4:5]
	v_cvt_pk_bf16_f32 v54, v66, v67
	v_cvt_pk_bf16_f32 v55, v68, v69
	v_cvt_pk_bf16_f32 v56, v70, v71
	v_cvt_pk_bf16_f32 v57, v72, v57
	v_exp_f32_e32 v80, v80
	v_add_f32_e32 v135, v67, v133
	s_waitcnt lgkmcnt(2)
; #define MFMA32(a, b, c) __builtin_amdgcn_mfma_f32_32x32x16_bf16((a), (b), (c), 0, 0, 0)
; DI int crow(int r, int hi) { return (r & 3) + 8 * (r >> 2) + 4 * hi; }
; DI void attn_prompt_unit(const Args& a, LAS unsigned char* lds, int b, int h, int qb, float cB, int tid, int lane, int wave) {
;     ...
;             for (int r = 0; r < 16; ++r) { const int kv = t * 64 + crow(r, h2);
;                 float e0 = __builtin_amdgcn_exp2f(p0[r]), e1 = __builtin_amdgcn_exp2f(p1[r]);
;                 if (diag) { if (kv > qloc) e0 = 0.f; if (kv + 32 > qloc) e1 = 0.f; }
;                 p0[r] = e0; p1[r] = e1; lsum += e0 + e1; }
; #pragma unroll
;             for (int s4 = 0; s4 < 4; ++s4) { const bf16x8 pf = (s4 < 2) ? pack8(p0, s4 & 1) : pack8(p1, s4 & 1);
;                 o0 = MFMA32(tr_frag(Vb, 96, 16 * s4 + 4 * h2, 16 * s4 + 8 + 4 * h2, 0, lane), pf, o0); o1 = MFMA32(tr_frag(Vb, 96, 16 * s4 + 4 * h2, 16 * s4 + 8 + 4 * h2, 32, lane), pf, o1); }
	v_mfma_f32_32x32x16_bf16 v[18:33], v[50:53], v[54:57], v[18:33]
	v_add_u32_e32 v50, 26, v119
	v_cmp_gt_i32_e32 vcc, v50, v178
	v_add_u32_e32 v50, 27, v119
	v_exp_f32_e32 v67, v81
	s_and_b64 s[4:5], s[20:21], vcc
	v_cmp_gt_i32_e32 vcc, v50, v178
	ds_read_b64_tr_b16 v[50:51], v79 offset:29696
	ds_read_b64_tr_b16 v[52:53], v79 offset:31232
	s_waitcnt lgkmcnt(2)
	v_mfma_f32_32x32x16_bf16 v[34:49], v[58:61], v[54:57], v[34:49]
	ds_read_b64_tr_b16 v[60:61], v79 offset:31296
	ds_read_b64_tr_b16 v[58:59], v79 offset:29760
	v_add_f32_e32 v129, v66, v121
	v_cndmask_b32_e64 v66, v80, 0, s[4:5]
	s_and_b64 s[4:5], s[20:21], vcc
	v_cndmask_b32_e64 v67, v67, 0, s[4:5]
	v_cvt_pk_bf16_f32 v54, v74, v75
	v_cvt_pk_bf16_f32 v55, v76, v77
	v_cvt_pk_bf16_f32 v56, v62, v194
	v_cvt_pk_bf16_f32 v57, v66, v67
	v_add_f32_e32 v1, v1, v129
	v_add_f32_e32 v139, v68, v137
	s_waitcnt lgkmcnt(2)
	v_mfma_f32_32x32x16_bf16 v[18:33], v[50:53], v[54:57], v[18:33]
	v_exp_f32_e32 v50, v63
	v_add_u32_e32 v51, 57, v119
	v_cmp_gt_i32_e32 vcc, v51, v178
	s_and_b64 s[4:5], s[20:21], vcc
	v_cndmask_b32_e64 v63, v50, 0, s[4:5]
	ds_read_b64_tr_b16 v[50:51], v79 offset:32768
	ds_read_b64_tr_b16 v[52:53], v79 offset:34304
	v_add_f32_e32 v1, v135, v1
	s_waitcnt lgkmcnt(2)
	v_mfma_f32_32x32x16_bf16 v[34:49], v[58:61], v[54:57], v[34:49]
	ds_read_b64_tr_b16 v[60:61], v79 offset:34368
	ds_read_b64_tr_b16 v[58:59], v79 offset:32832
	v_cvt_pk_bf16_f32 v54, v121, v133
	v_cvt_pk_bf16_f32 v55, v137, v157
	v_cvt_pk_bf16_f32 v56, v161, v171
	v_cvt_pk_bf16_f32 v57, v186, v73
	v_add_f32_e32 v159, v69, v157
	v_add_f32_e32 v1, v139, v1
	s_waitcnt lgkmcnt(2)
	v_mfma_f32_32x32x16_bf16 v[18:33], v[50:53], v[54:57], v[18:33]
	v_add_u32_e32 v50, 58, v119
	v_cmp_gt_i32_e32 vcc, v50, v178
	v_add_u32_e32 v50, 59, v119
	v_add_f32_e32 v169, v70, v161
	s_and_b64 s[4:5], s[20:21], vcc
	v_cmp_gt_i32_e32 vcc, v50, v178
	ds_read_b64_tr_b16 v[50:51], v79 offset:35840
	ds_read_b64_tr_b16 v[52:53], v79 offset:37376
	s_waitcnt lgkmcnt(2)
	v_mfma_f32_32x32x16_bf16 v[34:49], v[58:61], v[54:57], v[34:49]
	ds_read_b64_tr_b16 v[60:61], v79 offset:37440
	ds_read_b64_tr_b16 v[58:59], v79 offset:35904
	v_add_f32_e32 v1, v159, v1
	v_add_f32_e32 v179, v71, v171
	v_add_f32_e32 v1, v169, v1
	v_add_f32_e32 v187, v72, v186
	v_cndmask_b32_e64 v64, v64, 0, s[4:5]
	s_and_b64 s[4:5], s[20:21], vcc
	v_add_f32_e32 v1, v179, v1
	v_cndmask_b32_e64 v65, v65, 0, s[4:5]
	v_add_f32_e32 v1, v187, v1
	v_add_f32_e32 v190, v74, v189
	v_cvt_pk_bf16_f32 v54, v189, v191
	v_cvt_pk_bf16_f32 v55, v192, v193
	v_cvt_pk_bf16_f32 v56, v78, v63
	v_cvt_pk_bf16_f32 v57, v64, v65
	v_add_f32_e32 v1, v188, v1
	v_add_f32_e32 v1, v190, v1
	s_waitcnt lgkmcnt(2)
	v_mfma_f32_32x32x16_bf16 v[18:33], v[50:53], v[54:57], v[18:33]
	v_add_f32_e32 v50, v75, v191
	v_add_f32_e32 v51, v76, v192
	v_add_f32_e32 v1, v50, v1
	v_add_f32_e32 v52, v77, v193
	v_add_f32_e32 v1, v51, v1
	v_add_f32_e32 v53, v62, v78
	v_add_f32_e32 v1, v52, v1
	s_waitcnt lgkmcnt(0)
	v_mfma_f32_32x32x16_bf16 v[34:49], v[58:61], v[54:57], v[34:49]
	v_add_f32_e32 v62, v194, v63
	v_add_f32_e32 v1, v53, v1
	v_add_f32_e32 v63, v66, v64
	v_add_f32_e32 v1, v62, v1
	v_add_f32_e32 v64, v67, v65
	v_add_f32_e32 v1, v63, v1
	v_add_f32_e32 v1, v64, v1
	s_branch .LBB0_843
; #define LAS __attribute__((address_space(3)))
; #define MFMA32(a, b, c) __builtin_amdgcn_mfma_f32_32x32x16_bf16((a), (b), (c), 0, 0, 0)
; DI int crow(int r, int hi) { return (r & 3) + 8 * (r >> 2) + 4 * hi; }
; DI void attn_prompt_unit(const Args& a, LAS unsigned char* lds, int b, int h, int qb, float cB, int tid, int lane, int wave) {
;     ...
;         if (t * 64 <= qmax_w) {
;             const LAS bf16* Kb = Ks + buf * 6656; const LAS bf16* Vb = Vs + buf * 6144;
;             f32x16 p0, p1;
; #pragma unroll
;             for (int r = 0; r < 16; ++r) { p0[r] = -cB; p1[r] = -cB; }
; #pragma unroll
;             for (int s = 0; s < 6; ++s) { const bf16x8 k0 = *(const LAS bf16x8*)(Kb + r32 * 104 + 16 * s + 8 * h2), k1f = *(const LAS bf16x8*)(Kb + (32 + r32) * 104 + 16 * s + 8 * h2);
;                 p0 = MFMA32(k0, qf[s], p0); p1 = MFMA32(k1f, qf[s], p1); }
;             const bool diag = (t * 64 + 63 > qb * 256 + wave * 32);
; #pragma unroll
;             for (int r = 0; r < 16; ++r) { const int kv = t * 64 + crow(r, h2);
;                 float e0 = __builtin_amdgcn_exp2f(p0[r]), e1 = __builtin_amdgcn_exp2f(p1[r]);
;                 if (diag) { if (kv > qloc) e0 = 0.f; if (kv + 32 > qloc) e1 = 0.f; }
;                 p0[r] = e0; p1[r] = e1; lsum += e0 + e1; }
; #pragma unroll
;             for (int s4 = 0; s4 < 4; ++s4) { const bf16x8 pf = (s4 < 2) ? pack8(p0, s4 & 1) : pack8(p1, s4 & 1);
;                 o0 = MFMA32(tr_frag(Vb, 96, 16 * s4 + 4 * h2, 16 * s4 + 8 + 4 * h2, 0, lane), pf, o0); o1 = MFMA32(tr_frag(Vb, 96, 16 * s4 + 4 * h2, 16 * s4 + 8 + 4 * h2, 32, lane), pf, o1); }
.Lpa_fast_0:
	s_mul_i32 s4, s36, 0x3400
	v_add3_u32 v119, s4, v227, v126
	v_add3_u32 v121, s4, v228, v126
	s_mul_i32 s37, s36, 0x3000
	ds_read_b128 v[50:53], v119
	ds_read_b128 v[54:57], v119 offset:32
	ds_read_b128 v[58:61], v119 offset:64
	ds_read_b128 v[62:65], v119 offset:96
	ds_read_b128 v[186:189], v119 offset:128
	ds_read_b128 v[190:193], v119 offset:160
	ds_read_b128 v[194:197], v121
	s_waitcnt lgkmcnt(6)
	v_mfma_f32_32x32x16_bf16 v[66:81], v[50:53], v[86:89], v[2:17]
	s_waitcnt lgkmcnt(5)
	v_mfma_f32_32x32x16_bf16 v[66:81], v[54:57], v[90:93], v[66:81]
	s_waitcnt lgkmcnt(4)
	v_mfma_f32_32x32x16_bf16 v[66:81], v[58:61], v[94:97], v[66:81]
	s_waitcnt lgkmcnt(3)
	v_mfma_f32_32x32x16_bf16 v[66:81], v[62:65], v[98:101], v[66:81]
	s_waitcnt lgkmcnt(2)
	v_mfma_f32_32x32x16_bf16 v[66:81], v[186:189], v[106:109], v[66:81]
	ds_read_b128 v[186:189], v121 offset:32
	s_waitcnt lgkmcnt(2)
	v_mfma_f32_32x32x16_bf16 v[66:81], v[190:193], v[102:105], v[66:81]
	ds_read_b128 v[190:193], v121 offset:64
	v_add_u32_e32 v119, s37, v229
	s_waitcnt lgkmcnt(2)
	v_mfma_f32_32x32x16_bf16 v[50:65], v[194:197], v[86:89], v[2:17]
	ds_read_b128 v[194:197], v121 offset:96
	s_waitcnt lgkmcnt(2)
	v_mfma_f32_32x32x16_bf16 v[50:65], v[186:189], v[90:93], v[50:65]
	ds_read_b128 v[186:189], v121 offset:128
	s_waitcnt lgkmcnt(2)
	v_mfma_f32_32x32x16_bf16 v[50:65], v[190:193], v[94:97], v[50:65]
	ds_read_b128 v[190:193], v121 offset:160
	s_waitcnt lgkmcnt(2)
	v_mfma_f32_32x32x16_bf16 v[50:65], v[194:197], v[98:101], v[50:65]
	v_exp_f32_e32 v66, v66
	v_exp_f32_e32 v67, v67
	v_exp_f32_e32 v68, v68
	v_exp_f32_e32 v69, v69
	s_waitcnt lgkmcnt(1)
	v_mfma_f32_32x32x16_bf16 v[50:65], v[186:189], v[106:109], v[50:65]
	v_exp_f32_e32 v70, v70
	v_exp_f32_e32 v71, v71
	v_exp_f32_e32 v72, v72
	v_exp_f32_e32 v73, v73
	s_waitcnt lgkmcnt(0)
	v_mfma_f32_32x32x16_bf16 v[50:65], v[190:193], v[102:105], v[50:65]
	v_exp_f32_e32 v74, v74
	v_exp_f32_e32 v75, v75
	v_exp_f32_e32 v76, v76
	v_exp_f32_e32 v77, v77
	v_exp_f32_e32 v78, v78
	v_exp_f32_e32 v79, v79
	v_exp_f32_e32 v80, v80
	v_exp_f32_e32 v81, v81
	ds_read_b64_tr_b16 v[186:187], v119 offset:26624
	ds_read_b64_tr_b16 v[188:189], v119 offset:28160
	ds_read_b64_tr_b16 v[194:195], v119 offset:26688
	ds_read_b64_tr_b16 v[196:197], v119 offset:28224
	v_add_f32_e32 v1, v1, v66
	v_add_f32_e32 v1, v1, v67
	v_add_f32_e32 v1, v1, v68
	v_add_f32_e32 v1, v1, v69
	v_add_f32_e32 v1, v1, v70
	v_add_f32_e32 v1, v1, v71
	v_add_f32_e32 v1, v1, v72
	v_add_f32_e32 v1, v1, v73
	v_cvt_pk_bf16_f32 v66, v66, v67
	v_cvt_pk_bf16_f32 v67, v68, v69
	v_cvt_pk_bf16_f32 v68, v70, v71
	v_cvt_pk_bf16_f32 v69, v72, v73
	s_nop 0
	s_waitcnt lgkmcnt(0)
	v_mfma_f32_32x32x16_bf16 v[18:33], v[186:189], v[66:69], v[18:33]
	ds_read_b64_tr_b16 v[190:191], v119 offset:29696
	ds_read_b64_tr_b16 v[192:193], v119 offset:31232
	v_mfma_f32_32x32x16_bf16 v[34:49], v[194:197], v[66:69], v[34:49]
	ds_read_b64_tr_b16 v[186:187], v119 offset:29760
	ds_read_b64_tr_b16 v[188:189], v119 offset:31296
	v_exp_f32_e32 v50, v50
	v_exp_f32_e32 v51, v51
	v_exp_f32_e32 v52, v52
	v_exp_f32_e32 v53, v53
	v_exp_f32_e32 v54, v54
	v_exp_f32_e32 v55, v55
	v_exp_f32_e32 v56, v56
	v_exp_f32_e32 v57, v57
	v_add_f32_e32 v1, v1, v74
	v_add_f32_e32 v1, v1, v75
	v_add_f32_e32 v1, v1, v76
	v_add_f32_e32 v1, v1, v77
	v_add_f32_e32 v1, v1, v78
	v_add_f32_e32 v1, v1, v79
	v_add_f32_e32 v1, v1, v80
	v_add_f32_e32 v1, v1, v81
	v_cvt_pk_bf16_f32 v74, v74, v75
	v_cvt_pk_bf16_f32 v75, v76, v77
	v_cvt_pk_bf16_f32 v76, v78, v79
	v_cvt_pk_bf16_f32 v77, v80, v81
	s_nop 0
	s_waitcnt lgkmcnt(0)
	v_mfma_f32_32x32x16_bf16 v[18:33], v[190:193], v[74:77], v[18:33]
	ds_read_b64_tr_b16 v[194:195], v119 offset:32768
	ds_read_b64_tr_b16 v[196:197], v119 offset:34304
	v_mfma_f32_32x32x16_bf16 v[34:49], v[186:189], v[74:77], v[34:49]
	ds_read_b64_tr_b16 v[190:191], v119 offset:32832
	ds_read_b64_tr_b16 v[192:193], v119 offset:34368
	v_exp_f32_e32 v58, v58
	v_exp_f32_e32 v59, v59
	v_exp_f32_e32 v60, v60
	v_exp_f32_e32 v61, v61
	v_exp_f32_e32 v62, v62
	v_exp_f32_e32 v63, v63
	v_exp_f32_e32 v64, v64
	v_exp_f32_e32 v65, v65
	v_add_f32_e32 v121, v50, v51
	v_add_f32_e32 v121, v121, v52
	v_add_f32_e32 v121, v121, v53
	v_add_f32_e32 v121, v121, v54
	v_add_f32_e32 v121, v121, v55
	v_add_f32_e32 v121, v121, v56
	v_add_f32_e32 v121, v121, v57
	v_cvt_pk_bf16_f32 v50, v50, v51
	v_cvt_pk_bf16_f32 v51, v52, v53
	v_cvt_pk_bf16_f32 v52, v54, v55
	v_cvt_pk_bf16_f32 v53, v56, v57
	s_nop 0
	s_waitcnt lgkmcnt(0)
	v_mfma_f32_32x32x16_bf16 v[18:33], v[194:197], v[50:53], v[18:33]
	ds_read_b64_tr_b16 v[186:187], v119 offset:35840
	ds_read_b64_tr_b16 v[188:189], v119 offset:37376
	v_mfma_f32_32x32x16_bf16 v[34:49], v[190:193], v[50:53], v[34:49]
	ds_read_b64_tr_b16 v[194:195], v119 offset:35904
	ds_read_b64_tr_b16 v[196:197], v119 offset:37440
	v_add_f32_e32 v121, v121, v58
	v_add_f32_e32 v121, v121, v59
	v_add_f32_e32 v121, v121, v60
	v_add_f32_e32 v121, v121, v61
	v_add_f32_e32 v121, v121, v62
	v_add_f32_e32 v121, v121, v63
	v_add_f32_e32 v121, v121, v64
	v_add_f32_e32 v121, v121, v65
	v_cvt_pk_bf16_f32 v58, v58, v59
	v_cvt_pk_bf16_f32 v59, v60, v61
	v_cvt_pk_bf16_f32 v60, v62, v63
	v_cvt_pk_bf16_f32 v61, v64, v65
	s_nop 0
	s_waitcnt lgkmcnt(0)
	v_mfma_f32_32x32x16_bf16 v[18:33], v[186:189], v[58:61], v[18:33]
	v_add_f32_e32 v1, v1, v121
	v_mfma_f32_32x32x16_bf16 v[34:49], v[194:197], v[58:61], v[34:49]

; #define LAS __attribute__((address_space(3)))
; #define MFMA32(a, b, c) __builtin_amdgcn_mfma_f32_32x32x16_bf16((a), (b), (c), 0, 0, 0)
; DI int crow(int r, int hi) { return (r & 3) + 8 * (r >> 2) + 4 * hi; }
; DI void attn_prompt_unit(const Args& a, LAS unsigned char* lds, int b, int h, int qb, float cB, int tid, int lane, int wave) {
;     ...
;     for (int t = 0; t < NT; ++t) {
;         const int buf = t & 1;
;         if (t + 1 < NT) { const size_t kv1 = (size_t)(t + 1) * 64;
;             kst0 = *(const u32x4*)(kbase + (kv1 + kr0) * 768 + kp0 * 8); if (k1) kst1 = *(const u32x4*)(kbase + (kv1 + kr1) * 768 + kp1 * 8); vst = *(const u32x4*)(vbase + kv1 * 1024); }
;         if (t * 64 <= qmax_w) {
;             const LAS bf16* Kb = Ks + buf * 6656; const LAS bf16* Vb = Vs + buf * 6144;
;             f32x16 p0, p1;
; #pragma unroll
;             for (int r = 0; r < 16; ++r) { p0[r] = -cB; p1[r] = -cB; }
; #pragma unroll
;             for (int s = 0; s < 6; ++s) { const bf16x8 k0 = *(const LAS bf16x8*)(Kb + r32 * 104 + 16 * s + 8 * h2), k1f = *(const LAS bf16x8*)(Kb + (32 + r32) * 104 + 16 * s + 8 * h2);
;                 p0 = MFMA32(k0, qf[s], p0); p1 = MFMA32(k1f, qf[s], p1); }
;             const bool diag = (t * 64 + 63 > qb * 256 + wave * 32);
; #pragma unroll
;             for (int r = 0; r < 16; ++r) { const int kv = t * 64 + crow(r, h2);
;                 float e0 = __builtin_amdgcn_exp2f(p0[r]), e1 = __builtin_amdgcn_exp2f(p1[r]);
;                 if (diag) { if (kv > qloc) e0 = 0.f; if (kv + 32 > qloc) e1 = 0.f; }
;                 p0[r] = e0; p1[r] = e1; lsum += e0 + e1; }
; #pragma unroll
;             for (int s4 = 0; s4 < 4; ++s4) { const bf16x8 pf = (s4 < 2) ? pack8(p0, s4 & 1) : pack8(p1, s4 & 1);
;                 o0 = MFMA32(tr_frag(Vb, 96, 16 * s4 + 4 * h2, 16 * s4 + 8 + 4 * h2, 0, lane), pf, o0); o1 = MFMA32(tr_frag(Vb, 96, 16 * s4 + 4 * h2, 16 * s4 + 8 + 4 * h2, 32, lane), pf, o1); }
.LBB0_855:
	s_or_b64 exec, exec, s[4:5]
	global_load_dwordx4 v[114:117], v[162:163], off
	s_and_b32 s28, s27, 1
	s_cmp_gt_i32 s21, s19
	s_cbranch_scc1 .LBB0_857
	s_add_i32 s4, s21, 63
	s_cmp_gt_i32 s4, s20
	s_cselect_b64 s[16:17], -1, 0
	s_cbranch_scc0 .Lpa_fast_1
	s_mul_i32 s4, s28, 0x3400
	s_add_i32 s4, s4, 0
	v_add3_u32 v119, s4, v227, v126
	ds_read_b128 v[50:53], v119
	ds_read_b128 v[168:171], v119 offset:32
	v_add3_u32 v121, s4, v228, v126
	ds_read_b128 v[172:175], v121
	ds_read_b128 v[180:183], v121 offset:32
	s_add_i32 s4, s21, 63
	s_cmp_gt_i32 s4, s20
	s_cselect_b64 s[16:17], -1, 0
	s_mul_i32 s29, s28, 0x3000
	s_waitcnt lgkmcnt(3)
	v_mfma_f32_32x32x16_bf16 v[66:81], v[50:53], v[86:89], v[2:17]
	s_waitcnt lgkmcnt(1)
	v_mfma_f32_32x32x16_bf16 v[50:65], v[172:175], v[86:89], v[2:17]
	v_mfma_f32_32x32x16_bf16 v[66:81], v[168:171], v[90:93], v[66:81]
	ds_read_b128 v[168:171], v119 offset:64
	ds_read_b128 v[172:175], v119 offset:96
	s_waitcnt lgkmcnt(2)
	v_mfma_f32_32x32x16_bf16 v[50:65], v[180:183], v[90:93], v[50:65]
	s_waitcnt lgkmcnt(1)
	v_mfma_f32_32x32x16_bf16 v[66:81], v[168:171], v[94:97], v[66:81]
	ds_read_b128 v[168:171], v121 offset:64
	ds_read_b128 v[180:183], v121 offset:96
	s_waitcnt lgkmcnt(1)
	v_mfma_f32_32x32x16_bf16 v[50:65], v[168:171], v[94:97], v[50:65]
	v_mfma_f32_32x32x16_bf16 v[66:81], v[172:175], v[98:101], v[66:81]
	ds_read_b128 v[168:171], v119 offset:128
	ds_read_b128 v[172:175], v119 offset:160
	v_add_u32_e32 v119, s21, v118
	v_cmp_gt_i32_e32 vcc, v119, v178
	s_and_b64 s[30:31], s[16:17], vcc
	v_cmp_ge_i32_e32 vcc, v119, v178
	s_waitcnt lgkmcnt(2)
	v_mfma_f32_32x32x16_bf16 v[50:65], v[180:183], v[98:101], v[50:65]
	s_waitcnt lgkmcnt(1)
	v_mfma_f32_32x32x16_bf16 v[66:81], v[168:171], v[106:109], v[66:81]
	ds_read_b128 v[168:171], v121 offset:128
	ds_read_b128 v[180:183], v121 offset:160
	v_add_u32_e32 v121, 32, v119
	v_cmp_gt_i32_e64 s[4:5], v121, v178
	s_and_b64 s[4:5], s[16:17], s[4:5]
	s_waitcnt lgkmcnt(1)
	v_mfma_f32_32x32x16_bf16 v[50:65], v[168:171], v[106:109], v[50:65]
	s_waitcnt lgkmcnt(0)
	v_mfma_f32_32x32x16_bf16 v[50:65], v[180:183], v[102:105], v[50:65]
	v_mfma_f32_32x32x16_bf16 v[66:81], v[172:175], v[102:105], v[66:81]
	s_nop 10
	v_exp_f32_e32 v50, v50
	v_exp_f32_e32 v51, v51
	v_exp_f32_e32 v52, v52
	v_exp_f32_e32 v64, v64
	v_cndmask_b32_e64 v121, v50, 0, s[4:5]
	v_exp_f32_e32 v65, v65
	v_exp_f32_e32 v66, v66
	v_exp_f32_e32 v50, v67
	v_add_u32_e32 v67, 33, v119
	v_cmp_gt_i32_e64 s[4:5], v67, v178
	v_cndmask_b32_e64 v66, v66, 0, s[30:31]
	s_and_b64 s[30:31], s[16:17], vcc
	s_and_b64 s[4:5], s[16:17], s[4:5]
	v_cndmask_b32_e64 v67, v50, 0, s[30:31]
	v_cndmask_b32_e64 v133, v51, 0, s[4:5]
	v_add_u32_e32 v50, 2, v119
	v_exp_f32_e32 v51, v68
	v_cmp_gt_i32_e32 vcc, v50, v178
	v_add_u32_e32 v50, 34, v119
	v_cmp_gt_i32_e64 s[4:5], v50, v178
	s_and_b64 s[30:31], s[16:17], vcc
	s_and_b64 s[4:5], s[16:17], s[4:5]
	v_cndmask_b32_e64 v68, v51, 0, s[30:31]
	v_cndmask_b32_e64 v137, v52, 0, s[4:5]
	v_add_u32_e32 v50, 3, v119
	v_exp_f32_e32 v51, v69
	v_exp_f32_e32 v52, v53
	v_cmp_gt_i32_e32 vcc, v50, v178
	v_add_u32_e32 v50, 35, v119
	v_cmp_gt_i32_e64 s[4:5], v50, v178
	s_and_b64 s[30:31], s[16:17], vcc
	s_and_b64 s[4:5], s[16:17], s[4:5]
	v_cndmask_b32_e64 v69, v51, 0, s[30:31]
	v_cndmask_b32_e64 v157, v52, 0, s[4:5]
	v_add_u32_e32 v50, 8, v119
	v_exp_f32_e32 v51, v70
	v_exp_f32_e32 v52, v54
	v_cmp_gt_i32_e32 vcc, v50, v178
	v_add_u32_e32 v50, 40, v119
	v_cmp_gt_i32_e64 s[4:5], v50, v178
	s_and_b64 s[30:31], s[16:17], vcc
	s_and_b64 s[4:5], s[16:17], s[4:5]
	v_cndmask_b32_e64 v70, v51, 0, s[30:31]
	v_cndmask_b32_e64 v161, v52, 0, s[4:5]
	v_add_u32_e32 v50, 9, v119
	v_exp_f32_e32 v51, v71
	v_exp_f32_e32 v52, v55
	v_cmp_gt_i32_e32 vcc, v50, v178
	v_add_u32_e32 v50, 41, v119
	v_cmp_gt_i32_e64 s[4:5], v50, v178
	s_and_b64 s[30:31], s[16:17], vcc
	s_and_b64 s[4:5], s[16:17], s[4:5]
	v_cndmask_b32_e64 v71, v51, 0, s[30:31]
	v_cndmask_b32_e64 v169, v52, 0, s[4:5]
	v_add_u32_e32 v50, 10, v119
	v_exp_f32_e32 v51, v72
	v_exp_f32_e32 v52, v56
	v_cmp_gt_i32_e32 vcc, v50, v178
	v_add_u32_e32 v50, 42, v119
	v_cmp_gt_i32_e64 s[4:5], v50, v178
	s_and_b64 s[30:31], s[16:17], vcc
	s_and_b64 s[4:5], s[16:17], s[4:5]
	v_cndmask_b32_e64 v72, v51, 0, s[30:31]
	v_cndmask_b32_e64 v171, v52, 0, s[4:5]
	v_add_u32_e32 v50, 11, v119
	v_exp_f32_e32 v51, v73
	v_exp_f32_e32 v52, v57
	v_cmp_gt_i32_e32 vcc, v50, v178
	v_add_u32_e32 v50, 43, v119
	v_cmp_gt_i32_e64 s[4:5], v50, v178
	s_and_b64 s[30:31], s[16:17], vcc
	s_and_b64 s[4:5], s[16:17], s[4:5]
	v_cndmask_b32_e64 v57, v51, 0, s[30:31]
	v_cndmask_b32_e64 v73, v52, 0, s[4:5]
	v_add_u32_e32 v50, 16, v119
	v_exp_f32_e32 v51, v74
	v_exp_f32_e32 v52, v58
	v_cmp_gt_i32_e32 vcc, v50, v178
	v_add_u32_e32 v50, 48, v119
	v_cmp_gt_i32_e64 s[4:5], v50, v178
	s_and_b64 s[30:31], s[16:17], vcc
	s_and_b64 s[4:5], s[16:17], s[4:5]
	v_cndmask_b32_e64 v74, v51, 0, s[30:31]
	v_cndmask_b32_e64 v174, v52, 0, s[4:5]
	v_add_u32_e32 v50, 17, v119
	v_exp_f32_e32 v51, v75
	v_exp_f32_e32 v52, v59
	v_cmp_gt_i32_e32 vcc, v50, v178
	v_add_u32_e32 v50, 49, v119
	v_cmp_gt_i32_e64 s[4:5], v50, v178
	s_and_b64 s[30:31], s[16:17], vcc
	s_and_b64 s[4:5], s[16:17], s[4:5]
	v_cndmask_b32_e64 v75, v51, 0, s[30:31]
	v_cndmask_b32_e64 v179, v52, 0, s[4:5]
	v_add_u32_e32 v50, 18, v119
	v_exp_f32_e32 v51, v76
	v_exp_f32_e32 v52, v60
	v_cmp_gt_i32_e32 vcc, v50, v178
	v_add_u32_e32 v50, 50, v119
	v_cmp_gt_i32_e64 s[4:5], v50, v178
	s_and_b64 s[30:31], s[16:17], vcc
	s_and_b64 s[4:5], s[16:17], s[4:5]
	v_cndmask_b32_e64 v76, v51, 0, s[30:31]
	v_cndmask_b32_e64 v180, v52, 0, s[4:5]
	v_add_u32_e32 v50, 19, v119
	v_exp_f32_e32 v51, v77
	v_exp_f32_e32 v52, v61
	v_cmp_gt_i32_e32 vcc, v50, v178
	v_add_u32_e32 v50, 51, v119
	v_cmp_gt_i32_e64 s[4:5], v50, v178
	s_and_b64 s[30:31], s[16:17], vcc
	s_and_b64 s[4:5], s[16:17], s[4:5]
	v_cndmask_b32_e64 v77, v51, 0, s[30:31]
	v_cndmask_b32_e64 v181, v52, 0, s[4:5]
	v_add_u32_e32 v50, 24, v119
	v_exp_f32_e32 v51, v78
	v_exp_f32_e32 v52, v62
	v_cmp_gt_i32_e32 vcc, v50, v178
	v_add_u32_e32 v50, 56, v119
	v_cmp_gt_i32_e64 s[4:5], v50, v178
	s_and_b64 s[30:31], s[16:17], vcc
	s_and_b64 s[4:5], s[16:17], s[4:5]
	v_add_u32_e32 v50, 25, v119
	v_exp_f32_e32 v54, v79
	v_add_u32_e32 v79, s29, v229
	v_cndmask_b32_e64 v62, v51, 0, s[30:31]
	v_cndmask_b32_e64 v78, v52, 0, s[4:5]
	v_cmp_gt_i32_e32 vcc, v50, v178
	ds_read_b64_tr_b16 v[50:51], v79 offset:26624
	ds_read_b64_tr_b16 v[52:53], v79 offset:28160
	ds_read_b64_tr_b16 v[60:61], v79 offset:28224
	ds_read_b64_tr_b16 v[58:59], v79 offset:26688
	s_and_b64 s[4:5], s[16:17], vcc
	v_add_f32_e32 v173, v57, v73
	v_cndmask_b32_e64 v182, v54, 0, s[4:5]
	v_cvt_pk_bf16_f32 v54, v66, v67
	v_cvt_pk_bf16_f32 v55, v68, v69
	v_cvt_pk_bf16_f32 v56, v70, v71
	v_cvt_pk_bf16_f32 v57, v72, v57
	v_exp_f32_e32 v80, v80
	v_add_f32_e32 v135, v67, v133
	s_waitcnt lgkmcnt(2)
; #define MFMA32(a, b, c) __builtin_amdgcn_mfma_f32_32x32x16_bf16((a), (b), (c), 0, 0, 0)
; DI int crow(int r, int hi) { return (r & 3) + 8 * (r >> 2) + 4 * hi; }
; DI void attn_prompt_unit(const Args& a, LAS unsigned char* lds, int b, int h, int qb, float cB, int tid, int lane, int wave) {
;     ...
;             for (int r = 0; r < 16; ++r) { const int kv = t * 64 + crow(r, h2);
;                 float e0 = __builtin_amdgcn_exp2f(p0[r]), e1 = __builtin_amdgcn_exp2f(p1[r]);
;                 if (diag) { if (kv > qloc) e0 = 0.f; if (kv + 32 > qloc) e1 = 0.f; }
;                 p0[r] = e0; p1[r] = e1; lsum += e0 + e1; }
; #pragma unroll
;             for (int s4 = 0; s4 < 4; ++s4) { const bf16x8 pf = (s4 < 2) ? pack8(p0, s4 & 1) : pack8(p1, s4 & 1);
;                 o0 = MFMA32(tr_frag(Vb, 96, 16 * s4 + 4 * h2, 16 * s4 + 8 + 4 * h2, 0, lane), pf, o0); o1 = MFMA32(tr_frag(Vb, 96, 16 * s4 + 4 * h2, 16 * s4 + 8 + 4 * h2, 32, lane), pf, o1); }
	v_mfma_f32_32x32x16_bf16 v[18:33], v[50:53], v[54:57], v[18:33]
	v_add_u32_e32 v50, 26, v119
	v_cmp_gt_i32_e32 vcc, v50, v178
	v_add_u32_e32 v50, 27, v119
	v_exp_f32_e32 v67, v81
	s_and_b64 s[4:5], s[16:17], vcc
	v_cmp_gt_i32_e32 vcc, v50, v178
	ds_read_b64_tr_b16 v[50:51], v79 offset:29696
	ds_read_b64_tr_b16 v[52:53], v79 offset:31232
	s_waitcnt lgkmcnt(2)
	v_mfma_f32_32x32x16_bf16 v[34:49], v[58:61], v[54:57], v[34:49]
	ds_read_b64_tr_b16 v[60:61], v79 offset:31296
	ds_read_b64_tr_b16 v[58:59], v79 offset:29760
	v_add_f32_e32 v129, v66, v121
	v_cndmask_b32_e64 v66, v80, 0, s[4:5]
	s_and_b64 s[4:5], s[16:17], vcc
	v_cndmask_b32_e64 v67, v67, 0, s[4:5]
	v_cvt_pk_bf16_f32 v54, v74, v75
	v_cvt_pk_bf16_f32 v55, v76, v77
	v_cvt_pk_bf16_f32 v56, v62, v182
	v_cvt_pk_bf16_f32 v57, v66, v67
	v_add_f32_e32 v1, v1, v129
	v_add_f32_e32 v139, v68, v137
	s_waitcnt lgkmcnt(2)
	v_mfma_f32_32x32x16_bf16 v[18:33], v[50:53], v[54:57], v[18:33]
	v_exp_f32_e32 v50, v63
	v_add_u32_e32 v51, 57, v119
	v_cmp_gt_i32_e32 vcc, v51, v178
	s_and_b64 s[4:5], s[16:17], vcc
	v_cndmask_b32_e64 v63, v50, 0, s[4:5]
	ds_read_b64_tr_b16 v[50:51], v79 offset:32768
	ds_read_b64_tr_b16 v[52:53], v79 offset:34304
	v_add_f32_e32 v1, v135, v1
	s_waitcnt lgkmcnt(2)
	v_mfma_f32_32x32x16_bf16 v[34:49], v[58:61], v[54:57], v[34:49]
	ds_read_b64_tr_b16 v[60:61], v79 offset:34368
	ds_read_b64_tr_b16 v[58:59], v79 offset:32832
	v_cvt_pk_bf16_f32 v54, v121, v133
	v_cvt_pk_bf16_f32 v55, v137, v157
	v_cvt_pk_bf16_f32 v56, v161, v169
	v_cvt_pk_bf16_f32 v57, v171, v73
	v_add_f32_e32 v159, v69, v157
	v_add_f32_e32 v1, v139, v1
	s_waitcnt lgkmcnt(2)
	v_mfma_f32_32x32x16_bf16 v[18:33], v[50:53], v[54:57], v[18:33]
	v_add_u32_e32 v50, 58, v119
	v_cmp_gt_i32_e32 vcc, v50, v178
	v_add_u32_e32 v50, 59, v119
	v_add_f32_e32 v168, v70, v161
	s_and_b64 s[4:5], s[16:17], vcc
	v_cmp_gt_i32_e32 vcc, v50, v178
	ds_read_b64_tr_b16 v[50:51], v79 offset:35840
	ds_read_b64_tr_b16 v[52:53], v79 offset:37376
	s_waitcnt lgkmcnt(2)
	v_mfma_f32_32x32x16_bf16 v[34:49], v[58:61], v[54:57], v[34:49]
	ds_read_b64_tr_b16 v[60:61], v79 offset:37440
	ds_read_b64_tr_b16 v[58:59], v79 offset:35904
	v_add_f32_e32 v1, v159, v1
	v_add_f32_e32 v170, v71, v169
	v_add_f32_e32 v1, v168, v1
	v_add_f32_e32 v172, v72, v171
	v_cndmask_b32_e64 v64, v64, 0, s[4:5]
	s_and_b64 s[4:5], s[16:17], vcc
	v_add_f32_e32 v1, v170, v1
	v_cndmask_b32_e64 v65, v65, 0, s[4:5]
	v_add_f32_e32 v1, v172, v1
	v_add_f32_e32 v175, v74, v174
	v_cvt_pk_bf16_f32 v54, v174, v179
	v_cvt_pk_bf16_f32 v55, v180, v181
	v_cvt_pk_bf16_f32 v56, v78, v63
	v_cvt_pk_bf16_f32 v57, v64, v65
	v_add_f32_e32 v1, v173, v1
	v_add_f32_e32 v1, v175, v1
	s_waitcnt lgkmcnt(2)
	v_mfma_f32_32x32x16_bf16 v[18:33], v[50:53], v[54:57], v[18:33]
	v_add_f32_e32 v50, v75, v179
	v_add_f32_e32 v51, v76, v180
	v_add_f32_e32 v1, v50, v1
	v_add_f32_e32 v52, v77, v181
	v_add_f32_e32 v1, v51, v1
	v_add_f32_e32 v53, v62, v78
	v_add_f32_e32 v1, v52, v1
	s_waitcnt lgkmcnt(0)
	v_mfma_f32_32x32x16_bf16 v[34:49], v[58:61], v[54:57], v[34:49]
	v_add_f32_e32 v62, v182, v63
	v_add_f32_e32 v1, v53, v1
	v_add_f32_e32 v63, v66, v64
	v_add_f32_e32 v1, v62, v1
	v_add_f32_e32 v64, v67, v65
	v_add_f32_e32 v1, v63, v1
	v_add_f32_e32 v1, v64, v1
	s_branch .LBB0_857
; #define LAS __attribute__((address_space(3)))
; #define MFMA32(a, b, c) __builtin_amdgcn_mfma_f32_32x32x16_bf16((a), (b), (c), 0, 0, 0)
; DI int crow(int r, int hi) { return (r & 3) + 8 * (r >> 2) + 4 * hi; }
; DI void attn_prompt_unit(const Args& a, LAS unsigned char* lds, int b, int h, int qb, float cB, int tid, int lane, int wave) {
;     ...
;         if (t * 64 <= qmax_w) {
;             const LAS bf16* Kb = Ks + buf * 6656; const LAS bf16* Vb = Vs + buf * 6144;
;             f32x16 p0, p1;
; #pragma unroll
;             for (int r = 0; r < 16; ++r) { p0[r] = -cB; p1[r] = -cB; }
; #pragma unroll
;             for (int s = 0; s < 6; ++s) { const bf16x8 k0 = *(const LAS bf16x8*)(Kb + r32 * 104 + 16 * s + 8 * h2), k1f = *(const LAS bf16x8*)(Kb + (32 + r32) * 104 + 16 * s + 8 * h2);
;                 p0 = MFMA32(k0, qf[s], p0); p1 = MFMA32(k1f, qf[s], p1); }
;             const bool diag = (t * 64 + 63 > qb * 256 + wave * 32);
; #pragma unroll
;             for (int r = 0; r < 16; ++r) { const int kv = t * 64 + crow(r, h2);
;                 float e0 = __builtin_amdgcn_exp2f(p0[r]), e1 = __builtin_amdgcn_exp2f(p1[r]);
;                 if (diag) { if (kv > qloc) e0 = 0.f; if (kv + 32 > qloc) e1 = 0.f; }
;                 p0[r] = e0; p1[r] = e1; lsum += e0 + e1; }
; #pragma unroll
;             for (int s4 = 0; s4 < 4; ++s4) { const bf16x8 pf = (s4 < 2) ? pack8(p0, s4 & 1) : pack8(p1, s4 & 1);
;                 o0 = MFMA32(tr_frag(Vb, 96, 16 * s4 + 4 * h2, 16 * s4 + 8 + 4 * h2, 0, lane), pf, o0); o1 = MFMA32(tr_frag(Vb, 96, 16 * s4 + 4 * h2, 16 * s4 + 8 + 4 * h2, 32, lane), pf, o1); }
.Lpa_fast_1:
	s_mul_i32 s4, s28, 0x3400
	v_add3_u32 v119, s4, v227, v126
	v_add3_u32 v121, s4, v228, v126
	s_mul_i32 s29, s28, 0x3000
	ds_read_b128 v[50:53], v119
	ds_read_b128 v[54:57], v119 offset:32
	ds_read_b128 v[58:61], v119 offset:64
	ds_read_b128 v[62:65], v119 offset:96
	ds_read_b128 v[168:171], v119 offset:128
	ds_read_b128 v[172:175], v119 offset:160
	ds_read_b128 v[180:183], v121
	s_waitcnt lgkmcnt(6)
	v_mfma_f32_32x32x16_bf16 v[66:81], v[50:53], v[86:89], v[2:17]
	s_waitcnt lgkmcnt(5)
	v_mfma_f32_32x32x16_bf16 v[66:81], v[54:57], v[90:93], v[66:81]
	s_waitcnt lgkmcnt(4)
	v_mfma_f32_32x32x16_bf16 v[66:81], v[58:61], v[94:97], v[66:81]
	s_waitcnt lgkmcnt(3)
	v_mfma_f32_32x32x16_bf16 v[66:81], v[62:65], v[98:101], v[66:81]
	s_waitcnt lgkmcnt(2)
	v_mfma_f32_32x32x16_bf16 v[66:81], v[168:171], v[106:109], v[66:81]
	ds_read_b128 v[168:171], v121 offset:32
	s_waitcnt lgkmcnt(2)
	v_mfma_f32_32x32x16_bf16 v[66:81], v[172:175], v[102:105], v[66:81]
	ds_read_b128 v[172:175], v121 offset:64
	v_add_u32_e32 v119, s29, v229
	s_waitcnt lgkmcnt(2)
	v_mfma_f32_32x32x16_bf16 v[50:65], v[180:183], v[86:89], v[2:17]
	ds_read_b128 v[180:183], v121 offset:96
	s_waitcnt lgkmcnt(2)
	v_mfma_f32_32x32x16_bf16 v[50:65], v[168:171], v[90:93], v[50:65]
	ds_read_b128 v[168:171], v121 offset:128
	s_waitcnt lgkmcnt(2)
	v_mfma_f32_32x32x16_bf16 v[50:65], v[172:175], v[94:97], v[50:65]
	ds_read_b128 v[172:175], v121 offset:160
	s_waitcnt lgkmcnt(2)
	v_mfma_f32_32x32x16_bf16 v[50:65], v[180:183], v[98:101], v[50:65]
	v_exp_f32_e32 v66, v66
	v_exp_f32_e32 v67, v67
	v_exp_f32_e32 v68, v68
	v_exp_f32_e32 v69, v69
	s_waitcnt lgkmcnt(1)
	v_mfma_f32_32x32x16_bf16 v[50:65], v[168:171], v[106:109], v[50:65]
	v_exp_f32_e32 v70, v70
	v_exp_f32_e32 v71, v71
	v_exp_f32_e32 v72, v72
	v_exp_f32_e32 v73, v73
	s_waitcnt lgkmcnt(0)
	v_mfma_f32_32x32x16_bf16 v[50:65], v[172:175], v[102:105], v[50:65]
	v_exp_f32_e32 v74, v74
	v_exp_f32_e32 v75, v75
	v_exp_f32_e32 v76, v76
	v_exp_f32_e32 v77, v77
	v_exp_f32_e32 v78, v78
	v_exp_f32_e32 v79, v79
	v_exp_f32_e32 v80, v80
	v_exp_f32_e32 v81, v81
	ds_read_b64_tr_b16 v[168:169], v119 offset:26624
	ds_read_b64_tr_b16 v[170:171], v119 offset:28160
	ds_read_b64_tr_b16 v[180:181], v119 offset:26688
	ds_read_b64_tr_b16 v[182:183], v119 offset:28224
	v_add_f32_e32 v1, v1, v66
	v_add_f32_e32 v1, v1, v67
	v_add_f32_e32 v1, v1, v68
	v_add_f32_e32 v1, v1, v69
	v_add_f32_e32 v1, v1, v70
	v_add_f32_e32 v1, v1, v71
	v_add_f32_e32 v1, v1, v72
	v_add_f32_e32 v1, v1, v73
	v_cvt_pk_bf16_f32 v66, v66, v67
	v_cvt_pk_bf16_f32 v67, v68, v69
	v_cvt_pk_bf16_f32 v68, v70, v71
	v_cvt_pk_bf16_f32 v69, v72, v73
	s_nop 0
	s_waitcnt lgkmcnt(0)
	v_mfma_f32_32x32x16_bf16 v[18:33], v[168:171], v[66:69], v[18:33]
	ds_read_b64_tr_b16 v[172:173], v119 offset:29696
	ds_read_b64_tr_b16 v[174:175], v119 offset:31232
	v_mfma_f32_32x32x16_bf16 v[34:49], v[180:183], v[66:69], v[34:49]
	ds_read_b64_tr_b16 v[168:169], v119 offset:29760
	ds_read_b64_tr_b16 v[170:171], v119 offset:31296
	v_exp_f32_e32 v50, v50
	v_exp_f32_e32 v51, v51
	v_exp_f32_e32 v52, v52
	v_exp_f32_e32 v53, v53
	v_exp_f32_e32 v54, v54
	v_exp_f32_e32 v55, v55
	v_exp_f32_e32 v56, v56
	v_exp_f32_e32 v57, v57
	v_add_f32_e32 v1, v1, v74
	v_add_f32_e32 v1, v1, v75
	v_add_f32_e32 v1, v1, v76
	v_add_f32_e32 v1, v1, v77
	v_add_f32_e32 v1, v1, v78
	v_add_f32_e32 v1, v1, v79
	v_add_f32_e32 v1, v1, v80
	v_add_f32_e32 v1, v1, v81
	v_cvt_pk_bf16_f32 v74, v74, v75
	v_cvt_pk_bf16_f32 v75, v76, v77
	v_cvt_pk_bf16_f32 v76, v78, v79
	v_cvt_pk_bf16_f32 v77, v80, v81
	s_nop 0
	s_waitcnt lgkmcnt(0)
	v_mfma_f32_32x32x16_bf16 v[18:33], v[172:175], v[74:77], v[18:33]
	ds_read_b64_tr_b16 v[180:181], v119 offset:32768
	ds_read_b64_tr_b16 v[182:183], v119 offset:34304
	v_mfma_f32_32x32x16_bf16 v[34:49], v[168:171], v[74:77], v[34:49]
	ds_read_b64_tr_b16 v[172:173], v119 offset:32832
	ds_read_b64_tr_b16 v[174:175], v119 offset:34368
	v_exp_f32_e32 v58, v58
	v_exp_f32_e32 v59, v59
	v_exp_f32_e32 v60, v60
	v_exp_f32_e32 v61, v61
	v_exp_f32_e32 v62, v62
	v_exp_f32_e32 v63, v63
	v_exp_f32_e32 v64, v64
	v_exp_f32_e32 v65, v65
	v_add_f32_e32 v121, v50, v51
	v_add_f32_e32 v121, v121, v52
	v_add_f32_e32 v121, v121, v53
	v_add_f32_e32 v121, v121, v54
	v_add_f32_e32 v121, v121, v55
	v_add_f32_e32 v121, v121, v56
	v_add_f32_e32 v121, v121, v57
	v_cvt_pk_bf16_f32 v50, v50, v51
	v_cvt_pk_bf16_f32 v51, v52, v53
	v_cvt_pk_bf16_f32 v52, v54, v55
	v_cvt_pk_bf16_f32 v53, v56, v57
	s_nop 0
	s_waitcnt lgkmcnt(0)
	v_mfma_f32_32x32x16_bf16 v[18:33], v[180:183], v[50:53], v[18:33]
	ds_read_b64_tr_b16 v[168:169], v119 offset:35840
	ds_read_b64_tr_b16 v[170:171], v119 offset:37376
	v_mfma_f32_32x32x16_bf16 v[34:49], v[172:175], v[50:53], v[34:49]
	ds_read_b64_tr_b16 v[180:181], v119 offset:35904
	ds_read_b64_tr_b16 v[182:183], v119 offset:37440
	v_add_f32_e32 v121, v121, v58
	v_add_f32_e32 v121, v121, v59
	v_add_f32_e32 v121, v121, v60
	v_add_f32_e32 v121, v121, v61
	v_add_f32_e32 v121, v121, v62
	v_add_f32_e32 v121, v121, v63
	v_add_f32_e32 v121, v121, v64
	v_add_f32_e32 v121, v121, v65
	v_cvt_pk_bf16_f32 v58, v58, v59
	v_cvt_pk_bf16_f32 v59, v60, v61
	v_cvt_pk_bf16_f32 v60, v62, v63
	v_cvt_pk_bf16_f32 v61, v64, v65
	s_nop 0
	s_waitcnt lgkmcnt(0)
	v_mfma_f32_32x32x16_bf16 v[18:33], v[168:171], v[58:61], v[18:33]
	v_add_f32_e32 v1, v1, v121
	v_mfma_f32_32x32x16_bf16 v[34:49], v[180:183], v[58:61], v[34:49]
